# pass2 next-chunk loads issued at the loop top into spare VGPRs (v33 otherwise)
# speedup vs baseline: 1.0248x; 1.0248x over previous
.LBB0_483:
	s_or_b64 exec, exec, s[8:9]
	s_ashr_i32 s49, s36, 6
	s_ashr_i32 s50, s36, 7
	s_and_b64 s[8:9], s[4:5], exec
	s_cselect_b32 s8, s3, 0xb000000
	s_cselect_b32 s9, 0x200, s3
	s_add_u32 s8, s80, s8
	s_addc_u32 s10, s81, 0
	s_lshl_b32 s11, s7, 1
	s_add_u32 s37, s8, s11
	s_addc_u32 s38, s10, 0
	s_or_b32 s11, s7, s9
	s_ashr_i32 s7, s6, 31
	s_lshl_b64 s[8:9], s[6:7], 15
	s_add_u32 s8, s22, s8
	v_lshrrev_b32_e32 v2, 2, v32
	s_addc_u32 s9, s23, s9
	s_lshl_b32 s10, s49, 4
	v_and_b32_e32 v95, 12, v2
	v_or_b32_e32 v35, s10, v95
	v_lshlrev_b32_e32 v2, 7, v35
	s_waitcnt vmcnt(0)
	v_sub_f32_e32 v0, v0, v1
	v_ashrrev_i32_e32 v3, 31, v2
	v_and_b32_e32 v38, 15, v32
	v_mul_f32_e32 v0, 0x3fb8aa3b, v0
	v_lshl_add_u64 v[2:3], v[2:3], 1, s[8:9]
	v_lshlrev_b32_e32 v44, 1, v38
	v_exp_f32_e32 v0, v0
	v_lshl_add_u64 v[2:3], v[2:3], 0, v[44:45]
	global_load_ushort v4, v[2:3], off offset:256
	global_load_ushort v5, v[2:3], off
	global_load_ushort v6, v[2:3], off offset:768
	global_load_ushort v7, v[2:3], off offset:512
	global_load_ushort v8, v[2:3], off offset:288
	global_load_ushort v9, v[2:3], off offset:32
	global_load_ushort v10, v[2:3], off offset:800
	global_load_ushort v11, v[2:3], off offset:544
	global_load_ushort v12, v[2:3], off offset:320
	global_load_ushort v13, v[2:3], off offset:64
	global_load_ushort v14, v[2:3], off offset:832
	global_load_ushort v15, v[2:3], off offset:576
	global_load_ushort v16, v[2:3], off offset:352
	global_load_ushort v17, v[2:3], off offset:96
	global_load_ushort v18, v[2:3], off offset:864
	global_load_ushort v19, v[2:3], off offset:608
	global_load_ushort v20, v[2:3], off offset:384
	global_load_ushort v21, v[2:3], off offset:128
	global_load_ushort v22, v[2:3], off offset:896
	global_load_ushort v23, v[2:3], off offset:640
	global_load_ushort v36, v[2:3], off offset:416
	global_load_ushort v37, v[2:3], off offset:160
	global_load_ushort v39, v[2:3], off offset:928
	global_load_ushort v41, v[2:3], off offset:672
	global_load_ushort v42, v[2:3], off offset:448
	global_load_ushort v43, v[2:3], off offset:192
	global_load_ushort v47, v[2:3], off offset:960
	global_load_ushort v48, v[2:3], off offset:704
	global_load_ushort v49, v[2:3], off offset:480
	global_load_ushort v50, v[2:3], off offset:224
	global_load_ushort v51, v[2:3], off offset:992
	global_load_ushort v52, v[2:3], off offset:736
	s_lshl_b32 s6, s6, 7
	v_add_f32_e32 v0, 1.0, v0
	v_div_scale_f32 v1, s[8:9], v0, v0, 1.0
	s_lshl_b32 s51, s50, 4
	s_and_b32 s52, s6, 0xfffffc00
	s_or_b32 s53, s6, 0x3ff
	s_sub_i32 s8, s53, s51
	s_add_i32 s9, s51, s52
	s_and_b64 s[6:7], s[4:5], exec
	s_cselect_b32 s6, s9, s8
	s_mul_hi_i32 s7, s6, 0x1400
	s_mulk_i32 s6, 0x1400
	s_add_u32 s6, s82, s6
	s_addc_u32 s7, s83, s7
	s_or_b32 s8, s51, 1
	v_or_b32_e32 v40, s11, v33
	s_sub_i32 s11, s53, s8
	s_add_i32 s12, s8, s52
	s_and_b64 s[8:9], s[4:5], exec
	s_cselect_b32 s8, s12, s11
	s_mul_hi_i32 s9, s8, 0x1400
	s_mulk_i32 s8, 0x1400
	s_add_u32 s8, s82, s8
	s_addc_u32 s9, s83, s9
	s_or_b32 s11, s51, 2
	s_sub_i32 s14, s53, s11
	s_add_i32 s11, s11, s52
	s_and_b64 s[12:13], s[4:5], exec
	s_cselect_b32 s11, s11, s14
	s_mul_hi_i32 s13, s11, 0x1400
	s_mulk_i32 s11, 0x1400
	s_add_u32 s12, s82, s11
	s_addc_u32 s13, s83, s13
	s_or_b32 s11, s51, 3
	s_sub_i32 s16, s53, s11
	s_add_i32 s11, s11, s52
	s_and_b64 s[14:15], s[4:5], exec
	s_cselect_b32 s11, s11, s16
	s_mul_hi_i32 s15, s11, 0x1400
	s_mulk_i32 s11, 0x1400
	s_add_u32 s14, s82, s11
	s_addc_u32 s15, s83, s15
	s_or_b32 s11, s51, 4
	s_sub_i32 s18, s53, s11
	s_add_i32 s11, s11, s52
	s_and_b64 s[16:17], s[4:5], exec
	s_cselect_b32 s11, s11, s18
	s_mul_hi_i32 s17, s11, 0x1400
	s_mulk_i32 s11, 0x1400
	s_add_u32 s16, s82, s11
	s_addc_u32 s17, s83, s17
	s_or_b32 s11, s51, 5
	s_sub_i32 s24, s53, s11
	s_add_i32 s11, s11, s52
	s_and_b64 s[18:19], s[4:5], exec
	s_cselect_b32 s11, s11, s24
	s_mul_hi_i32 s19, s11, 0x1400
	s_mulk_i32 s11, 0x1400
	s_add_u32 s18, s82, s11
	s_addc_u32 s19, s83, s19
	s_or_b32 s11, s51, 6
	s_sub_i32 s26, s53, s11
	s_add_i32 s11, s11, s52
	s_and_b64 s[24:25], s[4:5], exec
	s_cselect_b32 s11, s11, s26
	s_mul_hi_i32 s25, s11, 0x1400
	s_mulk_i32 s11, 0x1400
	s_add_u32 s24, s82, s11
	s_addc_u32 s25, s83, s25
	s_or_b32 s11, s51, 7
	s_sub_i32 s28, s53, s11
	s_add_i32 s11, s11, s52
	s_and_b64 s[26:27], s[4:5], exec
	s_cselect_b32 s11, s11, s28
	s_mul_hi_i32 s27, s11, 0x1400
	s_mulk_i32 s11, 0x1400
	s_add_u32 s26, s82, s11
	s_addc_u32 s27, s83, s27
	s_or_b32 s11, s51, 8
	s_sub_i32 s30, s53, s11
	s_add_i32 s11, s11, s52
	s_and_b64 s[28:29], s[4:5], exec
	s_cselect_b32 s11, s11, s30
	s_mul_hi_i32 s29, s11, 0x1400
	s_mulk_i32 s11, 0x1400
	s_add_u32 s28, s82, s11
	s_addc_u32 s29, s83, s29
	s_or_b32 s11, s51, 9
	s_sub_i32 s34, s53, s11
	s_add_i32 s11, s11, s52
	s_and_b64 s[30:31], s[4:5], exec
	s_cselect_b32 s11, s11, s34
	s_mul_hi_i32 s31, s11, 0x1400
	s_mulk_i32 s11, 0x1400
	v_rcp_f32_e32 v2, v1
	s_add_u32 s30, s82, s11
	s_addc_u32 s31, s83, s31
	s_or_b32 s11, s51, 10
	s_sub_i32 s39, s53, s11
	s_add_i32 s11, s11, s52
	s_and_b64 s[34:35], s[4:5], exec
	v_fma_f32 v24, -v1, v2, 1.0
	s_cselect_b32 s11, s11, s39
	v_div_scale_f32 v3, vcc, 1.0, v0, 1.0
	v_fmac_f32_e32 v2, v24, v2
	s_mul_hi_i32 s35, s11, 0x1400
	s_mulk_i32 s11, 0x1400
	v_mul_f32_e32 v24, v3, v2
	s_add_u32 s34, s82, s11
	v_fma_f32 v25, -v1, v24, v3
	s_addc_u32 s35, s83, s35
	s_or_b32 s11, s51, 11
	v_fmac_f32_e32 v24, v25, v2
	s_sub_i32 s39, s53, s11
	s_add_i32 s11, s11, s52
	v_fma_f32 v1, -v1, v24, v3
	s_and_b64 s[54:55], s[4:5], exec
	v_div_fmas_f32 v1, v1, v2, v24
	s_cselect_b32 s11, s11, s39
	v_div_fixup_f32 v46, v1, v0, 1.0
	s_waitcnt vmcnt(31)
	v_lshlrev_b32_e32 v1, 16, v4
	s_waitcnt vmcnt(30)
	v_lshlrev_b32_e32 v0, 16, v5
	s_waitcnt vmcnt(29)
	v_lshlrev_b32_e32 v3, 16, v6
	s_waitcnt vmcnt(28)
	v_lshlrev_b32_e32 v2, 16, v7
	v_lshl_add_u32 v96, v35, 1, s33
	s_mul_hi_i32 s39, s11, 0x1400
	s_mulk_i32 s11, 0x1400
	s_waitcnt vmcnt(27)
	v_lshlrev_b32_e32 v5, 16, v8
	s_waitcnt vmcnt(26)
	v_lshlrev_b32_e32 v4, 16, v9
	s_waitcnt vmcnt(25)
	v_lshlrev_b32_e32 v7, 16, v10
	s_waitcnt vmcnt(24)
	v_lshlrev_b32_e32 v6, 16, v11
	s_waitcnt vmcnt(23)
	v_lshlrev_b32_e32 v25, 16, v12
	s_waitcnt vmcnt(22)
	v_lshlrev_b32_e32 v24, 16, v13
	s_waitcnt vmcnt(11)
	v_lshlrev_b32_e32 v13, 16, v36
	s_waitcnt vmcnt(10)
	v_lshlrev_b32_e32 v12, 16, v37
	v_cvt_pk_bf16_f32 v36, v0, v1
	v_cvt_pk_bf16_f32 v37, v2, v3
	v_mad_u32_u24 v35, v38, s40, v96
	s_add_u32 s54, s82, s11
	v_lshlrev_b32_e32 v27, 16, v14
	v_lshlrev_b32_e32 v26, 16, v15
	ds_write_b64 v35, v[36:37]
	v_cvt_pk_bf16_f32 v36, v4, v5
	v_cvt_pk_bf16_f32 v37, v6, v7
	s_addc_u32 s55, s83, s39
	s_or_b32 s11, s51, 12
	v_lshlrev_b32_e32 v29, 16, v16
	v_lshlrev_b32_e32 v28, 16, v17
	v_lshlrev_b32_e32 v31, 16, v18
	v_lshlrev_b32_e32 v30, 16, v19
	ds_write_b64 v35, v[36:37] offset:4352
	v_cvt_pk_bf16_f32 v36, v24, v25
	v_cvt_pk_bf16_f32 v37, v26, v27
	s_sub_i32 s39, s53, s11
	s_add_i32 s11, s11, s52
	v_lshlrev_b32_e32 v9, 16, v20
	v_lshlrev_b32_e32 v8, 16, v21
	v_lshlrev_b32_e32 v11, 16, v22
	v_lshlrev_b32_e32 v10, 16, v23
	ds_write_b64 v35, v[36:37] offset:8704
	v_cvt_pk_bf16_f32 v36, v28, v29
	v_cvt_pk_bf16_f32 v37, v30, v31
	s_and_b64 s[56:57], s[4:5], exec
	s_waitcnt vmcnt(9)
	v_lshlrev_b32_e32 v15, 16, v39
	s_waitcnt vmcnt(8)
	v_lshlrev_b32_e32 v14, 16, v41
	ds_write_b64 v35, v[36:37] offset:13056
	v_cvt_pk_bf16_f32 v36, v8, v9
	v_cvt_pk_bf16_f32 v37, v10, v11
	s_cselect_b32 s11, s11, s39
	s_waitcnt vmcnt(7)
	v_lshlrev_b32_e32 v17, 16, v42
	s_waitcnt vmcnt(6)
	v_lshlrev_b32_e32 v16, 16, v43
	s_waitcnt vmcnt(5)
	v_lshlrev_b32_e32 v19, 16, v47
	s_waitcnt vmcnt(4)
	v_lshlrev_b32_e32 v18, 16, v48
	ds_write_b64 v35, v[36:37] offset:17408
	v_cvt_pk_bf16_f32 v36, v12, v13
	v_cvt_pk_bf16_f32 v37, v14, v15
	s_mul_hi_i32 s39, s11, 0x1400
	s_mulk_i32 s11, 0x1400
	s_waitcnt vmcnt(3)
	v_lshlrev_b32_e32 v21, 16, v49
	s_waitcnt vmcnt(2)
	v_lshlrev_b32_e32 v20, 16, v50
	s_waitcnt vmcnt(1)
	v_lshlrev_b32_e32 v23, 16, v51
	s_waitcnt vmcnt(0)
	v_lshlrev_b32_e32 v22, 16, v52
	ds_write_b64 v35, v[36:37] offset:21760
	v_cvt_pk_bf16_f32 v36, v16, v17
	v_cvt_pk_bf16_f32 v37, v18, v19
	s_add_u32 s56, s82, s11
	ds_write_b64 v35, v[36:37] offset:26112
	v_cvt_pk_bf16_f32 v36, v20, v21
	v_cvt_pk_bf16_f32 v37, v22, v23
	s_addc_u32 s57, s83, s39
	s_or_b32 s11, s51, 13
	ds_write_b64 v35, v[36:37] offset:30464
	v_lshlrev_b32_e32 v98, 1, v34
	s_sub_i32 s39, s53, s11
	s_add_i32 s11, s11, s52
	global_load_ushort v99, v98, s[6:7] nt
	global_load_ushort v34, v98, s[6:7] offset:3072 nt
	global_load_ushort v100, v98, s[8:9] nt
	global_load_ushort v36, v98, s[8:9] offset:3072 nt
	global_load_ushort v101, v98, s[12:13] nt
	global_load_ushort v37, v98, s[12:13] offset:3072 nt
	global_load_ushort v102, v98, s[14:15] nt
	global_load_ushort v41, v98, s[14:15] offset:3072 nt
	global_load_ushort v103, v98, s[16:17] nt
	global_load_ushort v42, v98, s[16:17] offset:3072 nt
	global_load_ushort v104, v98, s[18:19] nt
	global_load_ushort v43, v98, s[18:19] offset:3072 nt
	global_load_ushort v105, v98, s[24:25] nt
	global_load_ushort v52, v98, s[24:25] offset:3072 nt
	global_load_ushort v117, v98, s[26:27] nt
	global_load_ushort v54, v98, s[26:27] offset:3072 nt
	global_load_ushort v134, v98, s[28:29] nt
	global_load_ushort v55, v98, s[28:29] offset:3072 nt
	global_load_ushort v136, v98, s[30:31] nt
	global_load_ushort v56, v98, s[30:31] offset:3072 nt
	global_load_ushort v137, v98, s[34:35] nt
	global_load_ushort v57, v98, s[34:35] offset:3072 nt
	global_load_ushort v140, v98, s[54:55] nt
	global_load_ushort v58, v98, s[54:55] offset:3072 nt
	s_and_b64 s[60:61], s[4:5], exec
	s_cselect_b32 s11, s11, s39
	s_mul_hi_i32 s39, s11, 0x1400
	s_mulk_i32 s11, 0x1400
	s_add_u32 s60, s82, s11
	s_addc_u32 s61, s83, s39
	s_or_b32 s11, s51, 14
	s_sub_i32 s39, s53, s11
	s_add_i32 s11, s11, s52
	s_and_b64 s[62:63], s[4:5], exec
	s_cselect_b32 s11, s11, s39
	s_mul_hi_i32 s39, s11, 0x1400
	s_mulk_i32 s11, 0x1400
	s_add_u32 s62, s82, s11
	s_addc_u32 s63, s83, s39
	s_or_b32 s11, s51, 15
	s_sub_i32 s39, s53, s11
	s_add_i32 s11, s11, s52
	s_and_b64 s[64:65], s[4:5], exec
	s_cselect_b32 s11, s11, s39
	s_mul_hi_i32 s39, s11, 0x1400
	s_mulk_i32 s11, 0x1400
	s_add_u32 s64, s82, s11
	v_lshlrev_b32_e32 v35, 1, v40
	s_addc_u32 s65, s83, s39
	global_load_ushort v147, v98, s[56:57] nt
	global_load_ushort v59, v98, s[56:57] offset:3072 nt
	global_load_ushort v150, v98, s[60:61] nt
	global_load_ushort v60, v98, s[60:61] offset:3072 nt
	global_load_ushort v152, v98, s[62:63] nt
	global_load_ushort v61, v98, s[62:63] offset:3072 nt
	global_load_ushort v154, v98, s[64:65] nt
	global_load_ushort v62, v98, s[64:65] offset:3072 nt
	global_load_ushort v106, v35, s[6:7] nt
	global_load_ushort v109, v35, s[8:9] nt
	global_load_ushort v115, v35, s[12:13] nt
	global_load_ushort v121, v35, s[14:15] nt
	global_load_ushort v129, v35, s[16:17] nt
	global_load_ushort v133, v35, s[18:19] nt
	global_load_ushort v135, v35, s[24:25] nt
	global_load_ushort v138, v35, s[26:27] nt
	global_load_ushort v139, v35, s[28:29] nt
	global_load_ushort v141, v35, s[30:31] nt
	global_load_ushort v142, v35, s[34:35] nt
	global_load_ushort v143, v35, s[54:55] nt
	global_load_ushort v149, v35, s[56:57] nt
	global_load_ushort v151, v35, s[60:61] nt
	global_load_ushort v153, v35, s[62:63] nt
	global_load_ushort v155, v35, s[64:65] nt
	s_lshl_b32 s6, s50, 9
	s_add_i32 s6, s41, s6
	s_lshl_b32 s54, s50, 5
	v_lshlrev_b32_e32 v35, 2, v33
	s_cmpk_lt_u32 s36, 0x80
	v_add_u32_e32 v107, s6, v35
	s_cselect_b64 s[6:7], -1, 0
	s_cmpk_gt_u32 s36, 0x7f
	s_cselect_b64 s[24:25], -1, 0
	s_cmp_eq_u32 s50, 1
	s_cselect_b64 s[26:27], -1, 0
	s_cmp_lg_u32 s50, 1
	s_cselect_b64 s[28:29], -1, 0
	s_cmp_eq_u32 s50, 2
	s_cselect_b64 s[8:9], -1, 0
	s_cmp_eq_u32 s50, 3
	v_lshl_add_u32 v110, v33, 1, 0
	s_cselect_b64 s[30:31], -1, 0
	s_cmp_lt_i32 s49, 10
	v_mad_u32_u24 v111, v33, s44, v110
	s_cselect_b64 s[34:35], -1, 0
	s_ashr_i32 s11, s10, 31
	v_mad_u32_u24 v63, v33, s43, v94
	v_mad_i32_i24 v64, v33, s45, v111
	v_or_b32_e32 v33, s10, v38
	s_lshl_b64 s[10:11], s[10:11], 1
	v_and_b32_e32 v53, 63, v32
	v_and_b32_e32 v112, 48, v32
	v_mul_lo_u32 v32, v33, s43
	s_add_u32 s10, s37, s10
	v_add_u32_e32 v66, s42, v32
	s_addc_u32 s11, s38, s11
	v_add_u32_e32 v67, 0, v32
	s_andn2_b32 s36, s36, 63
	v_or_b32_e32 v32, 48, v53
	s_add_i32 s56, s46, s36
	v_mul_u32_u24_e32 v68, 0x90, v32
	v_or_b32_e32 v32, 0x70, v53
	v_mul_u32_u24_e32 v53, 0x90, v32
	v_or_b32_e32 v32, 1, v95
	s_and_b64 s[18:19], s[4:5], exec
	v_or_b32_e32 v39, 16, v38
	v_mul_lo_u32 v47, v33, s40
	v_cmp_gt_u32_e64 s[12:13], v38, v32
	v_or_b32_e32 v32, 2, v95
	s_cselect_b32 s57, 10, 9
	s_lshl_b32 s18, s49, 5
	v_sub_f32_e32 v48, 1.0, v46
	s_mul_i32 s55, s50, 0x1100
	v_add_u32_e32 v65, s33, v47
	v_add_u32_e32 v113, 0, v112
	v_add_u32_e32 v114, s1, v112
	v_add_u32_e32 v116, s42, v112
	v_cmp_gt_u32_e64 s[14:15], v38, v32
	v_or_b32_e32 v32, 3, v95
	v_mul_u32_u24_e32 v69, 0x90, v39
	s_add_i32 s18, s1, s18
	s_mul_i32 s58, s49, 0x1100
	s_mov_b32 s59, 0
	v_mul_u32_u24_e32 v97, 0x110, v38
	v_add_u32_e32 v108, s41, v35
	v_lshl_add_u64 v[50:51], s[10:11], 0, v[44:45]
	v_mul_u32_u24_e32 v118, 0x90, v38
	v_add_u32_e32 v119, s46, v35
	v_mad_u32_u24 v120, v38, s40, v113
	v_cmp_gt_u32_e64 s[10:11], v38, v95
	v_cmp_gt_u32_e64 s[16:17], v38, v32
	v_mov_b32_e32 v47, v46
	v_mov_b32_e32 v49, v48
	s_waitcnt vmcnt(44)
	v_perm_b32 v32, v36, v34, s47
	s_waitcnt vmcnt(40)
	v_perm_b32 v33, v41, v37, s47
	s_waitcnt vmcnt(36)
	v_perm_b32 v34, v43, v42, s47
	s_waitcnt vmcnt(32)
	v_perm_b32 v35, v54, v52, s47
	s_waitcnt vmcnt(28)
	v_perm_b32 v36, v56, v55, s47
	s_waitcnt vmcnt(24)
	v_perm_b32 v37, v58, v57, s47
	s_waitcnt vmcnt(20)
	v_perm_b32 v38, v60, v59, s47
	s_waitcnt vmcnt(16)
	v_perm_b32 v39, v62, v61, s47
	v_add_u32_e32 v122, s18, v44
	s_add_i32 s58, s58, 0x8800
	v_add_u32_e32 v123, s54, v63
	v_add_u32_e32 v124, s55, v64
	v_lshlrev_b32_e32 v125, 1, v40
	v_add_u32_e32 v126, v65, v112
	v_add_u32_e32 v127, v66, v112
	v_add_u32_e32 v128, v114, v69
	v_add_u32_e32 v130, v67, v112
	v_add_u32_e32 v131, v116, v68
	v_add_u32_e32 v132, v116, v53
	s_waitcnt vmcnt(0)
	s_branch .LBB0_485

.LBB0_485:
	s_cmp_eq_u32 s59, 15
	s_cbranch_scc1 .Lp2_nopf
	s_lshl_b32 s98, s59, 6
	s_add_i32 s98, s98, 64
	s_add_i32 s98, s98, s51
	s_sub_i32 s99, s53, s98
	s_add_i32 s98, s98, s52
	s_and_b64 s[100:101], s[4:5], exec
	s_cselect_b32 s98, s98, s99
	s_movk_i32 s100, 0x1400
	s_cselect_b32 s100, s100, 0xffffec00
	s_mul_hi_i32 s99, s98, 0x1400
	s_mulk_i32 s98, 0x1400
	s_add_u32 s98, s82, s98
	s_addc_u32 s99, s83, s99
	s_ashr_i32 s101, s100, 31
	global_load_ushort v190, v125, s[98:99] nt
	global_load_ushort v206, v98, s[98:99] nt
	global_load_ushort v222, v98, s[98:99] offset:3072 nt
	s_add_u32 s98, s98, s100
	s_addc_u32 s99, s99, s101
	global_load_ushort v191, v125, s[98:99] nt
	global_load_ushort v207, v98, s[98:99] nt
	global_load_ushort v223, v98, s[98:99] offset:3072 nt
	s_add_u32 s98, s98, s100
	s_addc_u32 s99, s99, s101
	global_load_ushort v192, v125, s[98:99] nt
	global_load_ushort v208, v98, s[98:99] nt
	global_load_ushort v224, v98, s[98:99] offset:3072 nt
	s_add_u32 s98, s98, s100
	s_addc_u32 s99, s99, s101
	global_load_ushort v193, v125, s[98:99] nt
	global_load_ushort v209, v98, s[98:99] nt
	global_load_ushort v225, v98, s[98:99] offset:3072 nt
	s_add_u32 s98, s98, s100
	s_addc_u32 s99, s99, s101
	global_load_ushort v194, v125, s[98:99] nt
	global_load_ushort v210, v98, s[98:99] nt
	global_load_ushort v226, v98, s[98:99] offset:3072 nt
	s_add_u32 s98, s98, s100
	s_addc_u32 s99, s99, s101
	global_load_ushort v195, v125, s[98:99] nt
	global_load_ushort v211, v98, s[98:99] nt
	global_load_ushort v227, v98, s[98:99] offset:3072 nt
	s_add_u32 s98, s98, s100
	s_addc_u32 s99, s99, s101
	global_load_ushort v196, v125, s[98:99] nt
	global_load_ushort v212, v98, s[98:99] nt
	global_load_ushort v228, v98, s[98:99] offset:3072 nt
	s_add_u32 s98, s98, s100
	s_addc_u32 s99, s99, s101
	global_load_ushort v197, v125, s[98:99] nt
	global_load_ushort v213, v98, s[98:99] nt
	global_load_ushort v229, v98, s[98:99] offset:3072 nt
	s_add_u32 s98, s98, s100
	s_addc_u32 s99, s99, s101
	global_load_ushort v198, v125, s[98:99] nt
	global_load_ushort v214, v98, s[98:99] nt
	global_load_ushort v230, v98, s[98:99] offset:3072 nt
	s_add_u32 s98, s98, s100
	s_addc_u32 s99, s99, s101
	global_load_ushort v199, v125, s[98:99] nt
	global_load_ushort v215, v98, s[98:99] nt
	global_load_ushort v231, v98, s[98:99] offset:3072 nt
	s_add_u32 s98, s98, s100
	s_addc_u32 s99, s99, s101
	global_load_ushort v200, v125, s[98:99] nt
	global_load_ushort v216, v98, s[98:99] nt
	global_load_ushort v232, v98, s[98:99] offset:3072 nt
	s_add_u32 s98, s98, s100
	s_addc_u32 s99, s99, s101
	global_load_ushort v201, v125, s[98:99] nt
	global_load_ushort v217, v98, s[98:99] nt
	global_load_ushort v233, v98, s[98:99] offset:3072 nt
	s_add_u32 s98, s98, s100
	s_addc_u32 s99, s99, s101
	global_load_ushort v202, v125, s[98:99] nt
	global_load_ushort v218, v98, s[98:99] nt
	global_load_ushort v234, v98, s[98:99] offset:3072 nt
	s_add_u32 s98, s98, s100
	s_addc_u32 s99, s99, s101
	global_load_ushort v203, v125, s[98:99] nt
	global_load_ushort v219, v98, s[98:99] nt
	global_load_ushort v235, v98, s[98:99] offset:3072 nt
	s_add_u32 s98, s98, s100
	s_addc_u32 s99, s99, s101
	global_load_ushort v204, v125, s[98:99] nt
	global_load_ushort v220, v98, s[98:99] nt
	global_load_ushort v236, v98, s[98:99] offset:3072 nt
	s_add_u32 s98, s98, s100
	s_addc_u32 s99, s99, s101
	global_load_ushort v205, v125, s[98:99] nt
	global_load_ushort v221, v98, s[98:99] nt
	global_load_ushort v237, v98, s[98:99] offset:3072 nt
.Lp2_nopf:
	v_lshlrev_b32_e32 v42, 16, v115
	v_mul_f32_e32 v42, 0xbfb8aa3b, v42
	v_exp_f32_e32 v44, v42
	v_lshlrev_b32_e32 v42, 16, v121
	v_mul_f32_e32 v42, 0xbfb8aa3b, v42
	v_lshlrev_b32_e32 v40, 16, v106
	v_lshlrev_b32_e32 v41, 16, v109
	v_exp_f32_e32 v53, v42
	v_mul_f32_e32 v40, 0xbfb8aa3b, v40
	v_mul_f32_e32 v41, 0xbfb8aa3b, v41
	v_exp_f32_e32 v40, v40
	v_exp_f32_e32 v41, v41
	v_add_f32_e32 v44, 1.0, v44
	v_rcp_f32_e32 v52, v44
	v_add_f32_e32 v44, 1.0, v53
	v_lshlrev_b32_e32 v53, 16, v129
	v_mul_f32_e32 v53, 0xbfb8aa3b, v53
	v_add_f32_e32 v40, 1.0, v40
	v_add_f32_e32 v41, 1.0, v41
	v_exp_f32_e32 v54, v53
	v_lshlrev_b32_e32 v53, 16, v133
	v_rcp_f32_e32 v40, v40
	v_rcp_f32_e32 v41, v41
	v_mul_f32_e32 v53, 0xbfb8aa3b, v53
	v_exp_f32_e32 v55, v53
	v_rcp_f32_e32 v53, v44
	v_pk_fma_f32 v[40:41], v[48:49], v[40:41], v[46:47]
	v_add_f32_e32 v44, 1.0, v54
	v_pk_mul_f32 v[42:43], v[40:41], v[40:41] op_sel:[0,1] op_sel_hi:[1,0]
	v_pk_fma_f32 v[76:77], v[48:49], v[52:53], v[46:47]
	v_rcp_f32_e32 v56, v44
	v_add_f32_e32 v44, 1.0, v55
	v_pk_mul_f32 v[58:59], v[76:77], v[42:43]
	v_lshlrev_b32_e32 v43, 16, v135
	v_rcp_f32_e32 v57, v44
	v_mul_f32_e32 v43, 0xbfb8aa3b, v43
	v_lshlrev_b32_e32 v44, 16, v138
	v_exp_f32_e32 v43, v43
	v_mul_f32_e32 v44, 0xbfb8aa3b, v44
	v_exp_f32_e32 v44, v44
	v_pk_mul_f32 v[54:55], v[76:77], v[58:59] op_sel:[1,0] op_sel_hi:[0,1]
	v_pk_fma_f32 v[78:79], v[48:49], v[56:57], v[46:47]
	v_add_f32_e32 v43, 1.0, v43
	v_pk_mul_f32 v[52:53], v[78:79], v[54:55]
	v_rcp_f32_e32 v60, v43
	v_add_f32_e32 v43, 1.0, v44
	v_lshlrev_b32_e32 v44, 16, v139
	v_pk_mul_f32 v[56:57], v[78:79], v[52:53] op_sel:[1,0] op_sel_hi:[0,1]
	v_mul_f32_e32 v44, 0xbfb8aa3b, v44
	v_lshlrev_b32_e32 v53, 16, v141
	v_exp_f32_e32 v44, v44
	v_mul_f32_e32 v53, 0xbfb8aa3b, v53
	v_exp_f32_e32 v53, v53
	v_rcp_f32_e32 v61, v43
	v_add_f32_e32 v43, 1.0, v44
	v_rcp_f32_e32 v64, v43
	v_add_f32_e32 v43, 1.0, v53
	v_rcp_f32_e32 v65, v43
	v_lshlrev_b32_e32 v43, 16, v142
	v_mul_f32_e32 v43, 0xbfb8aa3b, v43
	v_lshlrev_b32_e32 v44, 16, v143
	v_exp_f32_e32 v43, v43
	v_mul_f32_e32 v44, 0xbfb8aa3b, v44
	v_exp_f32_e32 v44, v44
	v_lshlrev_b32_e32 v53, 16, v151
	v_add_f32_e32 v43, 1.0, v43
	v_rcp_f32_e32 v66, v43
	v_add_f32_e32 v43, 1.0, v44
	v_lshlrev_b32_e32 v44, 16, v149
	v_mul_f32_e32 v44, 0xbfb8aa3b, v44
	v_exp_f32_e32 v44, v44
	v_mul_f32_e32 v53, 0xbfb8aa3b, v53
	v_exp_f32_e32 v53, v53
	v_rcp_f32_e32 v67, v43
	v_add_f32_e32 v43, 1.0, v44
	v_rcp_f32_e32 v74, v43
	v_add_f32_e32 v43, 1.0, v53
	v_rcp_f32_e32 v75, v43
	v_lshlrev_b32_e32 v43, 16, v153
	v_mul_f32_e32 v43, 0xbfb8aa3b, v43
	v_lshlrev_b32_e32 v44, 16, v155
	v_exp_f32_e32 v43, v43
	v_mul_f32_e32 v44, 0xbfb8aa3b, v44
	v_pk_fma_f32 v[80:81], v[48:49], v[60:61], v[46:47]
	v_exp_f32_e32 v44, v44
	v_pk_mul_f32 v[68:69], v[80:81], v[56:57]
	v_pk_fma_f32 v[82:83], v[48:49], v[64:65], v[46:47]
	v_pk_mul_f32 v[62:63], v[80:81], v[68:69] op_sel:[1,0] op_sel_hi:[0,1]
	v_pk_mul_f32 v[60:61], v[82:83], v[62:63]
	v_add_f32_e32 v43, 1.0, v43
	v_pk_mul_f32 v[64:65], v[82:83], v[60:61] op_sel:[1,0] op_sel_hi:[0,1]
	v_pk_fma_f32 v[86:87], v[48:49], v[66:67], v[46:47]
	v_rcp_f32_e32 v43, v43
	v_add_f32_e32 v44, 1.0, v44
	v_pk_mul_f32 v[72:73], v[86:87], v[64:65]
	v_rcp_f32_e32 v44, v44
	v_pk_mul_f32 v[70:71], v[86:87], v[72:73] op_sel:[1,0] op_sel_hi:[0,1]
	v_pk_fma_f32 v[88:89], v[48:49], v[74:75], v[46:47]
	v_fma_f32 v92, v48, v43, v46
	v_pk_mul_f32 v[74:75], v[88:89], v[70:71]
	v_fma_f32 v93, v48, v44, v46
	v_mul_f32_e32 v55, v89, v74
	v_mul_f32_e32 v53, v92, v55
	v_mul_f32_e32 v43, v93, v53
	ds_write_b32 v107, v43
	ds_write_b128 v123, v[32:35]
	ds_write_b128 v123, v[36:39] offset:16
	s_waitcnt lgkmcnt(0)
	s_barrier
	ds_read2st64_b32 v[84:85], v108 offset1:2
	ds_read2st64_b32 v[66:67], v108 offset0:4 offset1:6
	v_cndmask_b32_e64 v44, 0, 1, s[24:25]
	v_cmp_ne_u32_e64 s[18:19], 1, v44
	s_andn2_b64 vcc, exec, s[24:25]
	v_mov_b32_e32 v57, 1.0
	s_cbranch_vccnz .LBB0_494
	s_cmp_lt_i32 s50, 2
	s_cbranch_scc1 .LBB0_490
	s_cmp_eq_u32 s50, 2
	s_mov_b64 s[36:37], -1
	s_cbranch_scc0 .LBB0_489
	s_waitcnt lgkmcnt(1)
	v_mul_f32_e32 v57, v84, v85
	s_mov_b64 s[36:37], 0

.LBB0_513:
	s_add_i32 s18, s59, 1
	s_cmp_eq_u32 s59, 15
	s_cbranch_scc1 .LBB0_515
	s_waitcnt vmcnt(0)
	v_mov_b32_e32 v106, v190
	v_mov_b32_e32 v109, v191
	v_mov_b32_e32 v115, v192
	v_mov_b32_e32 v121, v193
	v_mov_b32_e32 v129, v194
	v_mov_b32_e32 v133, v195
	v_mov_b32_e32 v135, v196
	v_mov_b32_e32 v138, v197
	v_mov_b32_e32 v139, v198
	v_mov_b32_e32 v141, v199
	v_mov_b32_e32 v142, v200
	v_mov_b32_e32 v143, v201
	v_mov_b32_e32 v149, v202
	v_mov_b32_e32 v151, v203
	v_mov_b32_e32 v153, v204
	v_mov_b32_e32 v155, v205
	v_mov_b32_e32 v99, v206
	v_mov_b32_e32 v100, v207
	v_mov_b32_e32 v101, v208
	v_mov_b32_e32 v102, v209
	v_mov_b32_e32 v103, v210
	v_mov_b32_e32 v104, v211
	v_mov_b32_e32 v105, v212
	v_mov_b32_e32 v117, v213
	v_mov_b32_e32 v134, v214
	v_mov_b32_e32 v136, v215
	v_mov_b32_e32 v137, v216
	v_mov_b32_e32 v140, v217
	v_mov_b32_e32 v147, v218
	v_mov_b32_e32 v150, v219
	v_mov_b32_e32 v152, v220
	v_mov_b32_e32 v154, v221
	v_perm_b32 v32, v223, v222, s47
	v_perm_b32 v33, v225, v224, s47
	v_perm_b32 v34, v227, v226, s47
	v_perm_b32 v35, v229, v228, s47
	v_perm_b32 v36, v231, v230, s47
	v_perm_b32 v37, v233, v232, s47
	v_perm_b32 v38, v235, v234, s47
	v_perm_b32 v39, v237, v236, s47
